# P1 conv tiles: conv weights/bias (5 KiB) LDS-DMA-prefetched during the K-loop (4 KiB extra static LDS); the conv epilogue's four vmcnt(0) drains become lgkmcnt(0)
# speedup vs baseline: 1.0047x; 1.0006x over previous
;     __device__ __forceinline__ void operator()(EPI_ARGS) const {
;     ...
;                 const int c0 = (pn - 4) * 256 + bj * 128 + wc * 32 + 8 * fq;
;                 f32x4 w0[2], w1[2], w2[2], w3[2], bb[2];
; #pragma unroll
;                 for (int n = 0; n < 2; ++n) { w0[n] = *(const f32x4*)(cw + c0 + 4 * n); w1[n] = *(const f32x4*)(cw + LW + c0 + 4 * n); w2[n] = *(const f32x4*)(cw + 2 * LW + c0 + 4 * n); w3[n] = *(const f32x4*)(cw + 3 * LW + c0 + 4 * n); bb[n] = *(const f32x4*)(cb + c0 + 4 * n); }
.Lp1pf_go:
	v_and_b32_e32 v222, 63, v212
	v_lshlrev_b32_e32 v222, 4, v222
	v_add_u32_e32 v222, s76, v222
	v_mov_b32_e32 v223, 0
	v_lshl_add_u64 v[220:221], v[220:221], 0, v[222:223]
	s_mov_b32 m0, 0x20400
	s_nop 0
	global_load_lds_dwordx4 v[220:221], off
	s_branch .Lp1pf_skip
.Lp1pf_conv:
	s_lshl_b32 s76, s76, 10
	v_and_b32_e32 v222, 63, v212
	v_lshlrev_b32_e32 v222, 4, v222
	v_add_u32_e32 v222, s76, v222
	v_mov_b32_e32 v223, 0
	v_mov_b32_e32 v220, s64
	v_mov_b32_e32 v221, s65
	v_lshl_add_u64 v[220:221], v[220:221], 0, v[222:223]
	s_mov_b32 m0, 0x20400
	s_nop 0
	global_load_lds_dwordx4 v[220:221], off
	v_mov_b32_e32 v220, s56
	v_mov_b32_e32 v221, s57
	v_lshl_add_u64 v[220:221], v[220:221], 0, v[222:223]
	s_mov_b32 m0, 0x20800
	s_nop 0
	global_load_lds_dwordx4 v[220:221], off
	v_mov_b32_e32 v220, s60
	v_mov_b32_e32 v221, s61
	v_lshl_add_u64 v[220:221], v[220:221], 0, v[222:223]
	s_mov_b32 m0, 0x20c00
	s_nop 0
	global_load_lds_dwordx4 v[220:221], off
	v_mov_b32_e32 v220, s16
	v_mov_b32_e32 v221, s17
	v_lshl_add_u64 v[220:221], v[220:221], 0, v[222:223]
	s_mov_b32 m0, 0x21000
	s_nop 0
	global_load_lds_dwordx4 v[220:221], off
	v_mov_b32_e32 v220, s66
	v_mov_b32_e32 v221, s67
	v_lshl_add_u64 v[220:221], v[220:221], 0, v[222:223]
	s_mov_b32 m0, 0x21400
	s_nop 0
	global_load_lds_dwordx4 v[220:221], off

;     __device__ __forceinline__ void operator()(EPI_ARGS) const {
;     ...
;                 const int c0 = (pn - 4) * 256 + bj * 128 + wc * 32 + 8 * fq;
;                 f32x4 w0[2], w1[2], w2[2], w3[2], bb[2];
; #pragma unroll
;                 for (int n = 0; n < 2; ++n) { w0[n] = *(const f32x4*)(cw + c0 + 4 * n); w1[n] = *(const f32x4*)(cw + LW + c0 + 4 * n); w2[n] = *(const f32x4*)(cw + 2 * LW + c0 + 4 * n); w3[n] = *(const f32x4*)(cw + 3 * LW + c0 + 4 * n); bb[n] = *(const f32x4*)(cb + c0 + 4 * n); }
; #pragma unroll
;                 for (int ai = 0; ai < 2; ++ai) {
;                     const int blk = u.pm * 4 + ai * 2 + wr;
;                     f32x4 q1[2], q2[2], q3[2];
; #pragma unroll
;                     for (int n = 0; n < 2; ++n) { q1[n] = (f32x4){0.f, 0.f, 0.f, 0.f}; q2[n] = q1[n]; q3[n] = q1[n]; }
; #pragma unroll
;                     for (int m = 0; m < 4; ++m) {
;                         const int row = ROW_OF(ai, m);
;                         f32x4 o[2];
; #pragma unroll
;                         for (int n = 0; n < 2; ++n) {
;                             const f32x4 gv = acc[ai][bj][m][n];
;                             f32x4 r1, r2, r3, p1, p2, p3;
; #pragma unroll
;                             for (int j = 0; j < 4; ++j) { r1[j] = __shfl(gv[j], s1); r2[j] = __shfl(gv[j], s2); r3[j] = __shfl(gv[j], s3); }
; #pragma unroll
;                             for (int j = 0; j < 4; ++j) { p1[j] = fr >= 1 ? r1[j] : q1[n][j]; p2[j] = fr >= 2 ? r2[j] : q2[n][j]; p3[j] = fr >= 3 ? r3[j] : q3[n][j]; }
;                             q1[n] = r1; q2[n] = r2; q3[n] = r3;
;                             o[n] = bb[n] + w0[n] * p3 + w1[n] * p2 + w2[n] * p1 + w3[n] * gv;
;                             if (m == 0 && fr < 3) *(f32x4*)(headu + ((size_t)blk * 3 + fr) * LW + c0 + 4 * n) = gv;
;                             if (m == 3 && fr >= 13) *(f32x4*)(tailu + ((size_t)blk * 3 + (fr - 13)) * LW + c0 + 4 * n) = gv;
;                         }
;                         if (!(m == 0 && fr < 3)) {
;                             u32x4 w; w.x = cvt_pk_bf16(o[0][0], o[0][1]); w.y = cvt_pk_bf16(o[0][2], o[0][3]); w.z = cvt_pk_bf16(o[1][0], o[1][1]); w.w = cvt_pk_bf16(o[1][2], o[1][3]);
;                             *(u32x4*)(vout + (size_t)row * LW + c0) = w;
.LBB0_135:
	s_and_b64 vcc, exec, s[0:1]
	s_cbranch_vccz .LBB0_339
	s_lshl_b32 s0, s13, 8
	s_add_i32 s0, s19, s0
	v_lshl_add_u32 v184, v176, 3, s0
	v_ashrrev_i32_e32 v185, 31, v184
	v_lshlrev_b64 v[128:129], 2, v[184:185]
	v_lshl_add_u64 v[192:193], s[64:65], 0, v[128:129]
	v_lshl_add_u64 v[130:131], s[56:57], 0, v[128:129]
	v_lshl_add_u64 v[132:133], s[60:61], 0, v[128:129]
	v_lshl_add_u64 v[144:145], s[16:17], 0, v[128:129]
	v_lshl_add_u64 v[190:191], s[66:67], 0, v[128:129]
	v_lshl_add_u32 v144, v207, 3, s27
	v_lshlrev_b32_e32 v144, 2, v144
	v_add_u32_e32 v144, 0x20400, v144
	ds_read_b128 v[160:163], v144 offset:16
	ds_read_b128 v[140:143], v144
	ds_read_b128 v[156:159], v144 offset:1040
	ds_read_b128 v[136:139], v144 offset:1024
	ds_read_b128 v[152:155], v144 offset:2064
	s_nop 0
	ds_read_b128 v[132:135], v144 offset:2048
	s_nop 0
	ds_read_b128 v[148:151], v144 offset:3088
	ds_read_b128 v[128:131], v144 offset:3072
	ds_read_b128 v[164:167], v144 offset:4112
	s_nop 0
	ds_read_b128 v[144:147], v144 offset:4096
	v_lshl_add_u32 v176, v176, 4, v182
	v_add_u32_e32 v183, -1, v182
	v_and_b32_e32 v176, 48, v176
	v_and_b32_e32 v183, 15, v183
	v_add_u32_e32 v186, 14, v182
	v_add_u32_e32 v187, 13, v182
	v_and_b32_e32 v186, 15, v186
	v_and_b32_e32 v187, 15, v187
	v_or3_b32 v183, v176, v183, v214
	v_lshlrev_b32_e32 v216, 2, v183
	v_or3_b32 v183, v176, v186, v214
	v_or3_b32 v176, v176, v187, v214
	s_lshl_b32 s34, s12, 2
	v_lshlrev_b32_e32 v217, 2, v183
	v_lshlrev_b32_e32 v218, 2, v176
	s_add_i32 s34, s34, s45
	v_ashrrev_i32_e32 v183, 31, v182
	s_nop 1
	v_mov_b32_dpp v219, v124 row_ror:1 row_mask:0xf bank_mask:0xf
	v_mov_b32_dpp v220, v124 row_ror:2 row_mask:0xf bank_mask:0xf
	v_mov_b32_dpp v221, v124 row_ror:3 row_mask:0xf bank_mask:0xf
	v_mov_b32_dpp v222, v125 row_ror:1 row_mask:0xf bank_mask:0xf
	v_mov_b32_dpp v223, v125 row_ror:2 row_mask:0xf bank_mask:0xf
	v_mov_b32_dpp v224, v125 row_ror:3 row_mask:0xf bank_mask:0xf
	v_mov_b32_dpp v225, v126 row_ror:1 row_mask:0xf bank_mask:0xf
	v_mov_b32_dpp v226, v126 row_ror:2 row_mask:0xf bank_mask:0xf
	v_mov_b32_dpp v227, v126 row_ror:3 row_mask:0xf bank_mask:0xf
	v_mov_b32_dpp v228, v127 row_ror:1 row_mask:0xf bank_mask:0xf
	v_mov_b32_dpp v229, v127 row_ror:2 row_mask:0xf bank_mask:0xf
	v_mov_b32_dpp v230, v127 row_ror:3 row_mask:0xf bank_mask:0xf
	v_mad_i64_i32 v[186:187], s[0:1], s34, 3, v[182:183]
	v_lshlrev_b64 v[186:187], 13, v[186:187]
	v_lshl_add_u64 v[186:187], s[50:51], 0, v[186:187]
	v_cmp_lt_i32_e64 s[8:9], 2, v182
	v_cmp_gt_i32_e64 s[10:11], 3, v182
	v_lshl_add_u64 v[188:189], v[184:185], 2, v[186:187]
	s_and_saveexec_b64 s[0:1], s[10:11]
	s_cbranch_execz .LBB0_138
	global_store_dwordx4 v[188:189], v[124:127], off
.LBB0_138:
	s_or_b64 exec, exec, s[0:1]
	s_nop 1
	v_mov_b32_dpp v194, v120 row_ror:1 row_mask:0xf bank_mask:0xf
	v_mov_b32_dpp v198, v120 row_ror:2 row_mask:0xf bank_mask:0xf
	v_mov_b32_dpp v202, v120 row_ror:3 row_mask:0xf bank_mask:0xf
	v_mov_b32_dpp v195, v121 row_ror:1 row_mask:0xf bank_mask:0xf
	v_mov_b32_dpp v199, v121 row_ror:2 row_mask:0xf bank_mask:0xf
	v_mov_b32_dpp v203, v121 row_ror:3 row_mask:0xf bank_mask:0xf
	v_mov_b32_dpp v196, v122 row_ror:1 row_mask:0xf bank_mask:0xf
	v_mov_b32_dpp v200, v122 row_ror:2 row_mask:0xf bank_mask:0xf
	v_mov_b32_dpp v204, v122 row_ror:3 row_mask:0xf bank_mask:0xf
	v_mov_b32_dpp v197, v123 row_ror:1 row_mask:0xf bank_mask:0xf
	v_mov_b32_dpp v201, v123 row_ror:2 row_mask:0xf bank_mask:0xf
	v_mov_b32_dpp v205, v123 row_ror:3 row_mask:0xf bank_mask:0xf
	s_lshl_b32 s0, s12, 8
	s_add_i32 s0, s0, s24
	v_add_u32_e32 v186, s0, v182
	v_cmp_lt_i32_e32 vcc, 0, v182
	v_cmp_lt_i32_e64 s[0:1], 1, v182
	v_cmp_lt_i32_e64 s[4:5], 2, v182
	v_ashrrev_i32_e32 v187, 31, v186
	s_and_saveexec_b64 s[6:7], s[8:9]
	s_xor_b64 s[6:7], exec, s[6:7]
	s_cbranch_execz .LBB0_140
	v_cndmask_b32_e64 v236, 0, v221, s[4:5]
	v_cndmask_b32_e64 v237, 0, v224, s[4:5]
	v_cndmask_b32_e64 v234, 0, v220, s[0:1]
	v_cndmask_b32_e64 v235, 0, v223, s[0:1]
	v_cndmask_b32_e64 v242, 0, v227, s[4:5]
	v_cndmask_b32_e64 v243, 0, v230, s[4:5]
	s_waitcnt lgkmcnt(0)
	v_pk_fma_f32 v[236:237], v[140:141], v[236:237], v[144:145]
	v_cndmask_b32_e32 v232, 0, v219, vcc
	v_cndmask_b32_e32 v233, 0, v222, vcc
	v_cndmask_b32_e64 v240, 0, v226, s[0:1]
	v_cndmask_b32_e64 v241, 0, v229, s[0:1]
	v_pk_fma_f32 v[242:243], v[142:143], v[242:243], v[146:147]
	v_pk_fma_f32 v[234:235], v[136:137], v[234:235], v[236:237]
	v_cndmask_b32_e32 v238, 0, v225, vcc
	v_cndmask_b32_e32 v239, 0, v228, vcc
	v_pk_fma_f32 v[240:241], v[138:139], v[240:241], v[242:243]
	v_pk_fma_f32 v[232:233], v[132:133], v[232:233], v[234:235]
	v_pk_fma_f32 v[234:235], v[134:135], v[238:239], v[240:241]
	v_pk_fma_f32 v[124:125], v[124:125], v[128:129], v[232:233]
	v_pk_fma_f32 v[232:233], v[162:163], v[204:205], v[166:167]
	v_pk_fma_f32 v[126:127], v[126:127], v[130:131], v[234:235]
	v_pk_fma_f32 v[234:235], v[160:161], v[202:203], v[164:165]
	v_pk_fma_f32 v[232:233], v[158:159], v[200:201], v[232:233]
	v_pk_fma_f32 v[234:235], v[156:157], v[198:199], v[234:235]
	v_pk_fma_f32 v[232:233], v[154:155], v[196:197], v[232:233]
	v_pk_fma_f32 v[234:235], v[152:153], v[194:195], v[234:235]
	v_pk_fma_f32 v[232:233], v[122:123], v[150:151], v[232:233]
	v_pk_fma_f32 v[234:235], v[120:121], v[148:149], v[234:235]
	v_cvt_pk_bf16_f32 v124, v124, v125
	v_cvt_pk_bf16_f32 v125, v126, v127
	s_nop 0
	v_cvt_pk_bf16_f32 v126, v234, v235
	v_cvt_pk_bf16_f32 v127, v232, v233
	v_lshlrev_b64 v[232:233], 12, v[186:187]
	v_lshl_add_u64 v[232:233], s[54:55], 0, v[232:233]
	v_lshl_add_u64 v[232:233], v[184:185], 1, v[232:233]
	global_store_dwordx4 v[232:233], v[124:127], off

; __device__ __forceinline__ unsigned cvt_pk_bf16(float lo, float hi) { unsigned r; asm volatile("v_cvt_pk_bf16_f32 %0, %1, %2" : "=v"(r) : "v"(lo), "v"(hi)); return r; }
;     __device__ __forceinline__ void operator()(EPI_ARGS) const {
;     ...
;                             const f32x4 gv = acc[ai][bj][m][n];
;                             f32x4 r1, r2, r3, p1, p2, p3;
; #pragma unroll
;                             for (int j = 0; j < 4; ++j) { r1[j] = __shfl(gv[j], s1); r2[j] = __shfl(gv[j], s2); r3[j] = __shfl(gv[j], s3); }
; #pragma unroll
;                             for (int j = 0; j < 4; ++j) { p1[j] = fr >= 1 ? r1[j] : q1[n][j]; p2[j] = fr >= 2 ? r2[j] : q2[n][j]; p3[j] = fr >= 3 ? r3[j] : q3[n][j]; }
;                             q1[n] = r1; q2[n] = r2; q3[n] = r3;
;                             o[n] = bb[n] + w0[n] * p3 + w1[n] * p2 + w2[n] * p1 + w3[n] * gv;
;                             if (m == 0 && fr < 3) *(f32x4*)(headu + ((size_t)blk * 3 + fr) * LW + c0 + 4 * n) = gv;
;                             if (m == 3 && fr >= 13) *(f32x4*)(tailu + ((size_t)blk * 3 + (fr - 13)) * LW + c0 + 4 * n) = gv;
;                         }
;                         if (!(m == 0 && fr < 3)) {
;                             u32x4 w; w.x = cvt_pk_bf16(o[0][0], o[0][1]); w.y = cvt_pk_bf16(o[0][2], o[0][3]); w.z = cvt_pk_bf16(o[1][0], o[1][1]); w.w = cvt_pk_bf16(o[1][2], o[1][3]);
;                             *(u32x4*)(vout + (size_t)row * LW + c0) = w;
.LBB0_142:
	s_or_b64 exec, exec, s[6:7]
	s_nop 1
	v_mov_b32_dpp v232, v116 row_ror:2 row_mask:0xf bank_mask:0xf
	v_mov_b32_dpp v236, v117 row_ror:3 row_mask:0xf bank_mask:0xf
	v_mov_b32_dpp v237, v118 row_ror:1 row_mask:0xf bank_mask:0xf
	v_mov_b32_dpp v239, v118 row_ror:3 row_mask:0xf bank_mask:0xf
	v_mov_b32_dpp v242, v119 row_ror:3 row_mask:0xf bank_mask:0xf
	v_mov_b32_dpp v234, v117 row_ror:1 row_mask:0xf bank_mask:0xf
	v_mov_b32_dpp v235, v117 row_ror:2 row_mask:0xf bank_mask:0xf
	v_mov_b32_dpp v238, v118 row_ror:2 row_mask:0xf bank_mask:0xf
	v_mov_b32_dpp v241, v119 row_ror:2 row_mask:0xf bank_mask:0xf
	v_mov_b32_dpp v233, v116 row_ror:3 row_mask:0xf bank_mask:0xf
	v_mov_b32_dpp v240, v119 row_ror:1 row_mask:0xf bank_mask:0xf
	v_mov_b32_dpp v231, v116 row_ror:1 row_mask:0xf bank_mask:0xf
	v_cndmask_b32_e64 v124, v220, v232, s[0:1]
	v_cndmask_b32_e64 v127, v224, v236, s[4:5]
	v_cndmask_b32_e32 v220, v225, v237, vcc
	v_cndmask_b32_e64 v224, v227, v239, s[4:5]
	v_cndmask_b32_e64 v225, v230, v242, s[4:5]
	v_cndmask_b32_e32 v123, v222, v234, vcc
	v_cndmask_b32_e64 v125, v223, v235, s[0:1]
	v_cndmask_b32_e64 v222, v226, v238, s[0:1]
	v_cndmask_b32_e64 v223, v229, v241, s[0:1]
	s_waitcnt lgkmcnt(0)
	v_pk_fma_f32 v[224:225], v[142:143], v[224:225], v[146:147]
	s_nop 1
	v_mov_b32_dpp v226, v112 row_ror:3 row_mask:0xf bank_mask:0xf
	v_mov_b32_dpp v229, v113 row_ror:3 row_mask:0xf bank_mask:0xf
	v_cndmask_b32_e64 v126, v221, v233, s[4:5]
	v_cndmask_b32_e32 v221, v228, v240, vcc
	v_pk_fma_f32 v[222:223], v[138:139], v[222:223], v[224:225]
	s_nop 1
	v_mov_b32_dpp v225, v112 row_ror:2 row_mask:0xf bank_mask:0xf
	v_mov_b32_dpp v228, v113 row_ror:2 row_mask:0xf bank_mask:0xf
	v_mov_b32_dpp v244, v114 row_ror:3 row_mask:0xf bank_mask:0xf
	v_mov_b32_dpp v247, v115 row_ror:3 row_mask:0xf bank_mask:0xf
	v_mov_b32_dpp v224, v112 row_ror:1 row_mask:0xf bank_mask:0xf
	v_mov_b32_dpp v227, v113 row_ror:1 row_mask:0xf bank_mask:0xf
	v_mov_b32_dpp v230, v114 row_ror:1 row_mask:0xf bank_mask:0xf
	v_mov_b32_dpp v243, v114 row_ror:2 row_mask:0xf bank_mask:0xf
	v_mov_b32_dpp v245, v115 row_ror:1 row_mask:0xf bank_mask:0xf
	v_mov_b32_dpp v246, v115 row_ror:2 row_mask:0xf bank_mask:0xf
	v_pk_fma_f32 v[126:127], v[140:141], v[126:127], v[144:145]
	v_cndmask_b32_e32 v122, v219, v231, vcc
	v_pk_fma_f32 v[124:125], v[136:137], v[124:125], v[126:127]
	v_cndmask_b32_e64 v126, v202, v226, s[4:5]
	v_pk_fma_f32 v[122:123], v[132:133], v[122:123], v[124:125]
	v_pk_fma_f32 v[124:125], v[134:135], v[220:221], v[222:223]
	v_cndmask_b32_e64 v127, v203, v229, s[4:5]
	v_pk_fma_f32 v[118:119], v[118:119], v[130:131], v[124:125]
	v_cndmask_b32_e64 v124, v198, v225, s[0:1]
	v_cndmask_b32_e64 v125, v199, v228, s[0:1]
	v_cndmask_b32_e64 v198, v204, v244, s[4:5]
	v_cndmask_b32_e64 v199, v205, v247, s[4:5]
	v_pk_fma_f32 v[126:127], v[160:161], v[126:127], v[164:165]
	v_pk_fma_f32 v[116:117], v[116:117], v[128:129], v[122:123]
	v_cndmask_b32_e32 v122, v194, v224, vcc
	v_cndmask_b32_e32 v123, v195, v227, vcc
	v_cndmask_b32_e32 v194, v196, v230, vcc
	v_cndmask_b32_e64 v196, v200, v243, s[0:1]
	v_cndmask_b32_e32 v195, v197, v245, vcc
	v_cndmask_b32_e64 v197, v201, v246, s[0:1]
	v_pk_fma_f32 v[198:199], v[162:163], v[198:199], v[166:167]
	v_pk_fma_f32 v[124:125], v[156:157], v[124:125], v[126:127]
	v_pk_fma_f32 v[196:197], v[158:159], v[196:197], v[198:199]
	v_pk_fma_f32 v[122:123], v[152:153], v[122:123], v[124:125]
	v_add_u32_e32 v126, 16, v186
	v_pk_fma_f32 v[124:125], v[154:155], v[194:195], v[196:197]
	v_pk_fma_f32 v[112:113], v[112:113], v[148:149], v[122:123]
	v_ashrrev_i32_e32 v127, 31, v126
	v_pk_fma_f32 v[114:115], v[114:115], v[150:151], v[124:125]
	v_cvt_pk_bf16_f32 v122, v116, v117
	v_cvt_pk_bf16_f32 v123, v118, v119
	v_cvt_pk_bf16_f32 v124, v112, v113
	v_lshlrev_b64 v[112:113], 12, v[126:127]
	v_lshl_add_u64 v[112:113], s[54:55], 0, v[112:113]
	v_lshlrev_b64 v[116:117], 1, v[184:185]
	v_cvt_pk_bf16_f32 v125, v114, v115
	v_lshl_add_u64 v[112:113], v[112:113], 0, v[116:117]
	global_store_dwordx4 v[112:113], v[122:125], off
	s_nop 1
	v_mov_b32_dpp v122, v108 row_ror:3 row_mask:0xf bank_mask:0xf
	v_mov_b32_dpp v125, v109 row_ror:3 row_mask:0xf bank_mask:0xf
	v_mov_b32_dpp v194, v110 row_ror:3 row_mask:0xf bank_mask:0xf
	v_mov_b32_dpp v197, v111 row_ror:3 row_mask:0xf bank_mask:0xf
	v_mov_b32_dpp v119, v108 row_ror:2 row_mask:0xf bank_mask:0xf
	v_mov_b32_dpp v124, v109 row_ror:2 row_mask:0xf bank_mask:0xf
	v_mov_b32_dpp v127, v110 row_ror:2 row_mask:0xf bank_mask:0xf
	v_mov_b32_dpp v196, v111 row_ror:2 row_mask:0xf bank_mask:0xf
; __device__ __forceinline__ unsigned cvt_pk_bf16(float lo, float hi) { unsigned r; asm volatile("v_cvt_pk_bf16_f32 %0, %1, %2" : "=v"(r) : "v"(lo), "v"(hi)); return r; }
;     __device__ __forceinline__ void operator()(EPI_ARGS) const {
;     ...
;                             const f32x4 gv = acc[ai][bj][m][n];
;                             f32x4 r1, r2, r3, p1, p2, p3;
; #pragma unroll
;                             for (int j = 0; j < 4; ++j) { r1[j] = __shfl(gv[j], s1); r2[j] = __shfl(gv[j], s2); r3[j] = __shfl(gv[j], s3); }
; #pragma unroll
;                             for (int j = 0; j < 4; ++j) { p1[j] = fr >= 1 ? r1[j] : q1[n][j]; p2[j] = fr >= 2 ? r2[j] : q2[n][j]; p3[j] = fr >= 3 ? r3[j] : q3[n][j]; }
;                             q1[n] = r1; q2[n] = r2; q3[n] = r3;
;                             o[n] = bb[n] + w0[n] * p3 + w1[n] * p2 + w2[n] * p1 + w3[n] * gv;
;                             if (m == 0 && fr < 3) *(f32x4*)(headu + ((size_t)blk * 3 + fr) * LW + c0 + 4 * n) = gv;
;                             if (m == 3 && fr >= 13) *(f32x4*)(tailu + ((size_t)blk * 3 + (fr - 13)) * LW + c0 + 4 * n) = gv;
;                         }
;                         if (!(m == 0 && fr < 3)) {
;                             u32x4 w; w.x = cvt_pk_bf16(o[0][0], o[0][1]); w.y = cvt_pk_bf16(o[0][2], o[0][3]); w.z = cvt_pk_bf16(o[1][0], o[1][1]); w.w = cvt_pk_bf16(o[1][2], o[1][3]);
;                             *(u32x4*)(vout + (size_t)row * LW + c0) = w;
	v_mov_b32_dpp v118, v108 row_ror:1 row_mask:0xf bank_mask:0xf
	v_mov_b32_dpp v123, v109 row_ror:1 row_mask:0xf bank_mask:0xf
	v_mov_b32_dpp v126, v110 row_ror:1 row_mask:0xf bank_mask:0xf
	v_mov_b32_dpp v195, v111 row_ror:1 row_mask:0xf bank_mask:0xf
	v_cndmask_b32_e64 v200, v233, v122, s[4:5]
	v_cndmask_b32_e64 v201, v236, v125, s[4:5]
	v_cndmask_b32_e64 v220, v239, v194, s[4:5]
	v_cndmask_b32_e64 v221, v242, v197, s[4:5]
	v_cndmask_b32_e64 v198, v232, v119, s[0:1]
	v_cndmask_b32_e64 v199, v235, v124, s[0:1]
	v_cndmask_b32_e64 v204, v238, v127, s[0:1]
	v_cndmask_b32_e64 v205, v241, v196, s[0:1]
	v_pk_fma_f32 v[200:201], v[140:141], v[200:201], v[144:145]
	v_pk_fma_f32 v[220:221], v[142:143], v[220:221], v[146:147]
	v_cndmask_b32_e32 v114, v231, v118, vcc
	v_cndmask_b32_e32 v115, v234, v123, vcc
	v_cndmask_b32_e32 v202, v237, v126, vcc
	v_cndmask_b32_e32 v203, v240, v195, vcc
	v_pk_fma_f32 v[204:205], v[138:139], v[204:205], v[220:221]
	v_pk_fma_f32 v[198:199], v[136:137], v[198:199], v[200:201]
	s_nop 1
	v_mov_b32_dpp v201, v105 row_ror:3 row_mask:0xf bank_mask:0xf
	v_pk_fma_f32 v[114:115], v[132:133], v[114:115], v[198:199]
	v_pk_fma_f32 v[198:199], v[134:135], v[202:203], v[204:205]
	s_nop 1
	v_mov_b32_dpp v200, v105 row_ror:2 row_mask:0xf bank_mask:0xf
	v_pk_fma_f32 v[222:223], v[110:111], v[130:131], v[198:199]
	s_nop 1
	v_mov_b32_dpp v198, v104 row_ror:3 row_mask:0xf bank_mask:0xf
	v_mov_b32_dpp v199, v105 row_ror:1 row_mask:0xf bank_mask:0xf
	v_mov_b32_dpp v110, v104 row_ror:1 row_mask:0xf bank_mask:0xf
	v_mov_b32_dpp v111, v104 row_ror:2 row_mask:0xf bank_mask:0xf
	v_mov_b32_dpp v204, v106 row_ror:3 row_mask:0xf bank_mask:0xf
	v_mov_b32_dpp v220, v107 row_ror:3 row_mask:0xf bank_mask:0xf
	v_mov_b32_dpp v202, v106 row_ror:1 row_mask:0xf bank_mask:0xf
	v_mov_b32_dpp v203, v106 row_ror:2 row_mask:0xf bank_mask:0xf
	v_mov_b32_dpp v219, v107 row_ror:2 row_mask:0xf bank_mask:0xf
	v_mov_b32_dpp v205, v107 row_ror:1 row_mask:0xf bank_mask:0xf
	v_pk_fma_f32 v[108:109], v[108:109], v[128:129], v[114:115]
	v_cndmask_b32_e64 v226, v226, v198, s[4:5]
	v_cndmask_b32_e32 v115, v227, v199, vcc
	v_cndmask_b32_e64 v227, v229, v201, s[4:5]
	v_cndmask_b32_e32 v114, v224, v110, vcc
	v_cndmask_b32_e64 v224, v225, v111, s[0:1]
	v_cndmask_b32_e64 v225, v228, v200, s[0:1]
	v_pk_fma_f32 v[226:227], v[160:161], v[226:227], v[164:165]
	v_cndmask_b32_e64 v232, v244, v204, s[4:5]
	v_cndmask_b32_e64 v233, v247, v220, s[4:5]
	v_pk_fma_f32 v[224:225], v[156:157], v[224:225], v[226:227]
	v_cndmask_b32_e32 v228, v230, v202, vcc
	v_cndmask_b32_e64 v230, v243, v203, s[0:1]
	v_cndmask_b32_e64 v231, v246, v219, s[0:1]
	v_pk_fma_f32 v[232:233], v[162:163], v[232:233], v[166:167]
	v_pk_fma_f32 v[114:115], v[152:153], v[114:115], v[224:225]
	v_cndmask_b32_e32 v229, v245, v205, vcc
	v_pk_fma_f32 v[230:231], v[158:159], v[230:231], v[232:233]
	v_pk_fma_f32 v[104:105], v[104:105], v[148:149], v[114:115]
	v_add_u32_e32 v114, 32, v186
	v_pk_fma_f32 v[224:225], v[154:155], v[228:229], v[230:231]
	v_ashrrev_i32_e32 v115, 31, v114
	v_pk_fma_f32 v[106:107], v[106:107], v[150:151], v[224:225]
	v_cvt_pk_bf16_f32 v230, v108, v109
	v_cvt_pk_bf16_f32 v231, v222, v223
	v_cvt_pk_bf16_f32 v232, v104, v105
	v_lshlrev_b64 v[104:105], 12, v[114:115]
	s_mul_hi_i32 s13, s34, 3
	s_mul_i32 s12, s34, 3
	v_add_u32_e32 v176, -13, v182
	v_cvt_pk_bf16_f32 v233, v106, v107
	v_lshl_add_u64 v[108:109], s[54:55], 0, v[104:105]
	s_nop 1
	v_mov_b32_dpp v104, v96 row_ror:1 row_mask:0xf bank_mask:0xf
	v_mov_b32_dpp v105, v96 row_ror:2 row_mask:0xf bank_mask:0xf
	v_mov_b32_dpp v106, v96 row_ror:3 row_mask:0xf bank_mask:0xf
	v_mov_b32_dpp v107, v97 row_ror:1 row_mask:0xf bank_mask:0xf
	v_mov_b32_dpp v221, v97 row_ror:2 row_mask:0xf bank_mask:0xf
	v_mov_b32_dpp v222, v97 row_ror:3 row_mask:0xf bank_mask:0xf
	v_mov_b32_dpp v223, v98 row_ror:1 row_mask:0xf bank_mask:0xf
	v_mov_b32_dpp v224, v98 row_ror:2 row_mask:0xf bank_mask:0xf
	v_mov_b32_dpp v225, v98 row_ror:3 row_mask:0xf bank_mask:0xf
	v_mov_b32_dpp v226, v99 row_ror:1 row_mask:0xf bank_mask:0xf
	v_mov_b32_dpp v227, v99 row_ror:2 row_mask:0xf bank_mask:0xf
	v_mov_b32_dpp v228, v99 row_ror:3 row_mask:0xf bank_mask:0xf
	v_lshl_add_u64 v[120:121], s[12:13], 0, v[176:177]
	v_lshlrev_b64 v[120:121], 13, v[120:121]
	v_lshl_add_u64 v[114:115], v[108:109], 0, v[116:117]
	v_lshl_add_u64 v[108:109], s[74:75], 0, v[120:121]
	v_cmp_lt_i32_e64 s[6:7], 12, v182
	v_lshl_add_u64 v[108:109], v[184:185], 2, v[108:109]
	global_store_dwordx4 v[114:115], v[230:233], off
	s_and_saveexec_b64 s[12:13], s[6:7]
	s_cbranch_execz .LBB0_144
	global_store_dwordx4 v[108:109], v[96:99], off

; __device__ __forceinline__ unsigned cvt_pk_bf16(float lo, float hi) { unsigned r; asm volatile("v_cvt_pk_bf16_f32 %0, %1, %2" : "=v"(r) : "v"(lo), "v"(hi)); return r; }
;     __device__ __forceinline__ void operator()(EPI_ARGS) const {
;     ...
;                 const int c0 = (pn - 4) * 256 + bj * 128 + wc * 32 + 8 * fq;
;                 f32x4 w0[2], w1[2], w2[2], w3[2], bb[2];
; #pragma unroll
;                 for (int n = 0; n < 2; ++n) { w0[n] = *(const f32x4*)(cw + c0 + 4 * n); w1[n] = *(const f32x4*)(cw + LW + c0 + 4 * n); w2[n] = *(const f32x4*)(cw + 2 * LW + c0 + 4 * n); w3[n] = *(const f32x4*)(cw + 3 * LW + c0 + 4 * n); bb[n] = *(const f32x4*)(cb + c0 + 4 * n); }
;     ...
;                             const f32x4 gv = acc[ai][bj][m][n];
;                             f32x4 r1, r2, r3, p1, p2, p3;
; #pragma unroll
;                             for (int j = 0; j < 4; ++j) { r1[j] = __shfl(gv[j], s1); r2[j] = __shfl(gv[j], s2); r3[j] = __shfl(gv[j], s3); }
; #pragma unroll
;                             for (int j = 0; j < 4; ++j) { p1[j] = fr >= 1 ? r1[j] : q1[n][j]; p2[j] = fr >= 2 ? r2[j] : q2[n][j]; p3[j] = fr >= 3 ? r3[j] : q3[n][j]; }
;                             q1[n] = r1; q2[n] = r2; q3[n] = r3;
;                             o[n] = bb[n] + w0[n] * p3 + w1[n] * p2 + w2[n] * p1 + w3[n] * gv;
;                             if (m == 0 && fr < 3) *(f32x4*)(headu + ((size_t)blk * 3 + fr) * LW + c0 + 4 * n) = gv;
;                             if (m == 3 && fr >= 13) *(f32x4*)(tailu + ((size_t)blk * 3 + (fr - 13)) * LW + c0 + 4 * n) = gv;
;                         }
;                         if (!(m == 0 && fr < 3)) {
;                             u32x4 w; w.x = cvt_pk_bf16(o[0][0], o[0][1]); w.y = cvt_pk_bf16(o[0][2], o[0][3]); w.z = cvt_pk_bf16(o[1][0], o[1][1]); w.w = cvt_pk_bf16(o[1][2], o[1][3]);
;                             *(u32x4*)(vout + (size_t)row * LW + c0) = w;
.LBB0_156:
	s_or_b64 exec, exec, s[12:13]
	v_cndmask_b32_e32 v76, v76, v88, vcc
	v_cndmask_b32_e64 v88, v77, v89, s[0:1]
	v_cndmask_b32_e64 v78, v78, v176, s[4:5]
	v_cndmask_b32_e32 v77, v79, v182, vcc
	v_cndmask_b32_e64 v79, v95, v194, s[4:5]
	v_cndmask_b32_e64 v89, v94, v183, s[0:1]
	v_pk_fma_f32 v[78:79], v[160:161], v[78:79], v[164:165]
	v_cndmask_b32_e64 v98, v98, v197, s[4:5]
	v_pk_fma_f32 v[78:79], v[156:157], v[88:89], v[78:79]
	v_cndmask_b32_e32 v95, v99, v198, vcc
	v_cndmask_b32_e64 v99, v101, v200, s[4:5]
	v_pk_fma_f32 v[76:77], v[152:153], v[76:77], v[78:79]
	v_cndmask_b32_e32 v94, v96, v195, vcc
	v_cndmask_b32_e64 v96, v97, v196, s[0:1]
	v_cndmask_b32_e64 v97, v100, v199, s[0:1]
	v_pk_fma_f32 v[98:99], v[162:163], v[98:99], v[166:167]
	v_pk_fma_f32 v[68:69], v[68:69], v[148:149], v[76:77]
	v_cndmask_b32_e64 v76, v81, v73, s[0:1]
	v_cndmask_b32_e64 v74, v82, v74, s[4:5]
	v_cndmask_b32_e32 v73, v83, v75, vcc
	v_cndmask_b32_e64 v75, v85, v103, s[4:5]
	v_pk_fma_f32 v[96:97], v[158:159], v[96:97], v[98:99]
	v_cndmask_b32_e64 v77, v84, v102, s[0:1]
	v_cndmask_b32_e64 v82, v90, v124, s[4:5]
	v_cndmask_b32_e64 v83, v93, v127, s[4:5]
	v_pk_fma_f32 v[74:75], v[140:141], v[74:75], v[144:145]
	v_pk_fma_f32 v[78:79], v[154:155], v[94:95], v[96:97]
	v_cndmask_b32_e32 v72, v80, v72, vcc
	v_cndmask_b32_e64 v80, v87, v123, s[0:1]
	v_cndmask_b32_e64 v81, v92, v126, s[0:1]
	v_pk_fma_f32 v[82:83], v[142:143], v[82:83], v[146:147]
	v_pk_fma_f32 v[74:75], v[136:137], v[76:77], v[74:75]
	v_pk_fma_f32 v[70:71], v[70:71], v[150:151], v[78:79]
	v_cndmask_b32_e32 v78, v86, v122, vcc
	v_cndmask_b32_e32 v79, v91, v125, vcc
	v_pk_fma_f32 v[80:81], v[138:139], v[80:81], v[82:83]
	v_pk_fma_f32 v[72:73], v[132:133], v[72:73], v[74:75]
	v_pk_fma_f32 v[74:75], v[134:135], v[78:79], v[80:81]
	v_pk_fma_f32 v[64:65], v[64:65], v[128:129], v[72:73]
	v_add_u32_e32 v72, 0xb0, v186
	v_pk_fma_f32 v[66:67], v[66:67], v[130:131], v[74:75]
	v_ashrrev_i32_e32 v73, 31, v72
	v_cvt_pk_bf16_f32 v64, v64, v65
	v_cvt_pk_bf16_f32 v65, v66, v67
	v_cvt_pk_bf16_f32 v66, v68, v69
	v_lshlrev_b64 v[68:69], 12, v[72:73]
	v_lshl_add_u64 v[68:69], s[54:55], 0, v[68:69]
	v_lshl_add_u64 v[122:123], v[184:185], 1, v[68:69]
	v_cvt_pk_bf16_f32 v67, v70, v71
	global_store_dwordx4 v[122:123], v[64:67], off
	s_nop 1
	v_mov_b32_dpp v136, v60 row_ror:1 row_mask:0xf bank_mask:0xf
	v_mov_b32_dpp v137, v60 row_ror:2 row_mask:0xf bank_mask:0xf
	v_add_u32_e32 v64, 0x80, v184
	v_ashrrev_i32_e32 v65, 31, v64
	v_lshlrev_b64 v[64:65], 2, v[64:65]
	v_lshl_add_u64 v[66:67], s[56:57], 0, v[64:65]
	v_lshl_add_u64 v[68:69], s[60:61], 0, v[64:65]
	v_lshl_add_u64 v[64:65], s[16:17], 0, v[64:65]
	v_lshl_add_u32 v80, v207, 3, s27
	v_lshlrev_b32_e32 v80, 2, v80
	v_add_u32_e32 v80, 0x20400, v80
	ds_read_b128 v[96:99], v80 offset:528
	ds_read_b128 v[76:79], v80 offset:512
	ds_read_b128 v[92:95], v80 offset:1552
	ds_read_b128 v[72:75], v80 offset:1536
	ds_read_b128 v[88:91], v80 offset:2576
	s_nop 0
	ds_read_b128 v[68:71], v80 offset:2560
	s_nop 0
	ds_read_b128 v[84:87], v80 offset:3600
	s_nop 0
	ds_read_b128 v[64:67], v80 offset:3584
	s_nop 0
	ds_read_b128 v[100:103], v80 offset:4624
	ds_read_b128 v[80:83], v80 offset:4608
	s_nop 1
	v_mov_b32_dpp v138, v60 row_ror:3 row_mask:0xf bank_mask:0xf
	v_mov_b32_dpp v139, v61 row_ror:1 row_mask:0xf bank_mask:0xf
	v_mov_b32_dpp v140, v61 row_ror:2 row_mask:0xf bank_mask:0xf
	v_mov_b32_dpp v141, v61 row_ror:3 row_mask:0xf bank_mask:0xf
	v_mov_b32_dpp v142, v62 row_ror:1 row_mask:0xf bank_mask:0xf
	v_mov_b32_dpp v143, v62 row_ror:2 row_mask:0xf bank_mask:0xf
	v_mov_b32_dpp v144, v62 row_ror:3 row_mask:0xf bank_mask:0xf
	v_mov_b32_dpp v145, v63 row_ror:1 row_mask:0xf bank_mask:0xf
	v_mov_b32_dpp v146, v63 row_ror:2 row_mask:0xf bank_mask:0xf
	v_mov_b32_dpp v147, v63 row_ror:3 row_mask:0xf bank_mask:0xf
	s_and_saveexec_b64 s[12:13], s[10:11]
	s_cbranch_execz .LBB0_158
	global_store_dwordx4 v[188:189], v[60:63], off offset:512
.LBB0_158:
	s_or_b64 exec, exec, s[12:13]
	s_nop 1
	v_mov_b32_dpp v124, v56 row_ror:1 row_mask:0xf bank_mask:0xf
	v_mov_b32_dpp v128, v56 row_ror:2 row_mask:0xf bank_mask:0xf
	v_mov_b32_dpp v132, v56 row_ror:3 row_mask:0xf bank_mask:0xf
	v_mov_b32_dpp v125, v57 row_ror:1 row_mask:0xf bank_mask:0xf
	v_mov_b32_dpp v129, v57 row_ror:2 row_mask:0xf bank_mask:0xf
	v_mov_b32_dpp v133, v57 row_ror:3 row_mask:0xf bank_mask:0xf
	v_mov_b32_dpp v126, v58 row_ror:1 row_mask:0xf bank_mask:0xf
	v_mov_b32_dpp v130, v58 row_ror:2 row_mask:0xf bank_mask:0xf
	v_mov_b32_dpp v134, v58 row_ror:3 row_mask:0xf bank_mask:0xf
	v_mov_b32_dpp v127, v59 row_ror:1 row_mask:0xf bank_mask:0xf
	v_mov_b32_dpp v131, v59 row_ror:2 row_mask:0xf bank_mask:0xf
	v_mov_b32_dpp v135, v59 row_ror:3 row_mask:0xf bank_mask:0xf
	s_and_saveexec_b64 s[12:13], s[8:9]
	s_xor_b64 s[34:35], exec, s[12:13]
	s_cbranch_execz .LBB0_160
	v_cndmask_b32_e64 v152, 0, v138, s[4:5]
	v_cndmask_b32_e64 v153, 0, v141, s[4:5]
	v_cndmask_b32_e64 v150, 0, v137, s[0:1]
	v_cndmask_b32_e64 v151, 0, v140, s[0:1]
	v_cndmask_b32_e64 v158, 0, v144, s[4:5]
	v_cndmask_b32_e64 v159, 0, v147, s[4:5]
	s_waitcnt lgkmcnt(0)
	v_pk_fma_f32 v[152:153], v[76:77], v[152:153], v[80:81]
	v_cndmask_b32_e32 v148, 0, v136, vcc
	v_cndmask_b32_e32 v149, 0, v139, vcc
	v_cndmask_b32_e64 v156, 0, v143, s[0:1]
	v_cndmask_b32_e64 v157, 0, v146, s[0:1]
	v_pk_fma_f32 v[158:159], v[78:79], v[158:159], v[82:83]
	v_pk_fma_f32 v[150:151], v[72:73], v[150:151], v[152:153]
	v_cndmask_b32_e32 v154, 0, v142, vcc
	v_cndmask_b32_e32 v155, 0, v145, vcc
	v_pk_fma_f32 v[156:157], v[74:75], v[156:157], v[158:159]
	v_pk_fma_f32 v[148:149], v[68:69], v[148:149], v[150:151]
	v_pk_fma_f32 v[150:151], v[70:71], v[154:155], v[156:157]
	v_pk_fma_f32 v[60:61], v[60:61], v[64:65], v[148:149]
	v_pk_fma_f32 v[148:149], v[98:99], v[134:135], v[102:103]
	v_pk_fma_f32 v[62:63], v[62:63], v[66:67], v[150:151]
	v_pk_fma_f32 v[150:151], v[96:97], v[132:133], v[100:101]
	v_pk_fma_f32 v[148:149], v[94:95], v[130:131], v[148:149]
	v_pk_fma_f32 v[150:151], v[92:93], v[128:129], v[150:151]
	v_pk_fma_f32 v[148:149], v[90:91], v[126:127], v[148:149]
	v_pk_fma_f32 v[150:151], v[88:89], v[124:125], v[150:151]
	v_pk_fma_f32 v[148:149], v[58:59], v[86:87], v[148:149]
	v_pk_fma_f32 v[150:151], v[56:57], v[84:85], v[150:151]
	v_cvt_pk_bf16_f32 v60, v60, v61
	v_cvt_pk_bf16_f32 v61, v62, v63
	s_nop 0
	v_cvt_pk_bf16_f32 v62, v150, v151
	v_cvt_pk_bf16_f32 v63, v148, v149
	v_lshlrev_b64 v[148:149], 12, v[186:187]
	v_lshl_add_u64 v[148:149], s[54:55], 0, v[148:149]
	v_lshl_add_u64 v[148:149], v[184:185], 1, v[148:149]
	global_store_dwordx4 v[148:149], v[60:63], off offset:256

;     __device__ __forceinline__ void operator()(EPI_ARGS) const {
;     ...
;                             const f32x4 gv = acc[ai][bj][m][n];
;                             f32x4 r1, r2, r3, p1, p2, p3;
; #pragma unroll
;                             for (int j = 0; j < 4; ++j) { r1[j] = __shfl(gv[j], s1); r2[j] = __shfl(gv[j], s2); r3[j] = __shfl(gv[j], s3); }
; #pragma unroll
;                             for (int j = 0; j < 4; ++j) { p1[j] = fr >= 1 ? r1[j] : q1[n][j]; p2[j] = fr >= 2 ? r2[j] : q2[n][j]; p3[j] = fr >= 3 ? r3[j] : q3[n][j]; }
;                             q1[n] = r1; q2[n] = r2; q3[n] = r3;
;                             o[n] = bb[n] + w0[n] * p3 + w1[n] * p2 + w2[n] * p1 + w3[n] * gv;
.LBB0_162:
	s_or_b64 exec, exec, s[12:13]
	s_nop 1
	v_mov_b32_dpp v150, v52 row_ror:3 row_mask:0xf bank_mask:0xf
	v_mov_b32_dpp v151, v53 row_ror:1 row_mask:0xf bank_mask:0xf
	v_mov_b32_dpp v156, v54 row_ror:3 row_mask:0xf bank_mask:0xf
	v_mov_b32_dpp v159, v55 row_ror:3 row_mask:0xf bank_mask:0xf
	v_mov_b32_dpp v148, v52 row_ror:1 row_mask:0xf bank_mask:0xf
	v_mov_b32_dpp v149, v52 row_ror:2 row_mask:0xf bank_mask:0xf
	v_mov_b32_dpp v152, v53 row_ror:2 row_mask:0xf bank_mask:0xf
	v_mov_b32_dpp v155, v54 row_ror:2 row_mask:0xf bank_mask:0xf
	v_mov_b32_dpp v158, v55 row_ror:2 row_mask:0xf bank_mask:0xf
	v_mov_b32_dpp v153, v53 row_ror:3 row_mask:0xf bank_mask:0xf
	v_mov_b32_dpp v154, v54 row_ror:1 row_mask:0xf bank_mask:0xf
	v_mov_b32_dpp v157, v55 row_ror:1 row_mask:0xf bank_mask:0xf
	v_cndmask_b32_e64 v60, v138, v150, s[4:5]
	v_cndmask_b32_e32 v57, v139, v151, vcc
	v_cndmask_b32_e64 v138, v144, v156, s[4:5]
	v_cndmask_b32_e64 v139, v147, v159, s[4:5]
	v_cndmask_b32_e32 v56, v136, v148, vcc
	v_cndmask_b32_e64 v58, v137, v149, s[0:1]
	v_cndmask_b32_e64 v59, v140, v152, s[0:1]
	v_cndmask_b32_e64 v136, v143, v155, s[0:1]
	v_cndmask_b32_e64 v137, v146, v158, s[0:1]
	s_waitcnt lgkmcnt(0)
; __device__ __forceinline__ unsigned cvt_pk_bf16(float lo, float hi) { unsigned r; asm volatile("v_cvt_pk_bf16_f32 %0, %1, %2" : "=v"(r) : "v"(lo), "v"(hi)); return r; }
;     __device__ __forceinline__ void operator()(EPI_ARGS) const {
;     ...
;                             const f32x4 gv = acc[ai][bj][m][n];
;                             f32x4 r1, r2, r3, p1, p2, p3;
; #pragma unroll
;                             for (int j = 0; j < 4; ++j) { r1[j] = __shfl(gv[j], s1); r2[j] = __shfl(gv[j], s2); r3[j] = __shfl(gv[j], s3); }
; #pragma unroll
;                             for (int j = 0; j < 4; ++j) { p1[j] = fr >= 1 ? r1[j] : q1[n][j]; p2[j] = fr >= 2 ? r2[j] : q2[n][j]; p3[j] = fr >= 3 ? r3[j] : q3[n][j]; }
;                             q1[n] = r1; q2[n] = r2; q3[n] = r3;
;                             o[n] = bb[n] + w0[n] * p3 + w1[n] * p2 + w2[n] * p1 + w3[n] * gv;
;                             if (m == 0 && fr < 3) *(f32x4*)(headu + ((size_t)blk * 3 + fr) * LW + c0 + 4 * n) = gv;
;                             if (m == 3 && fr >= 13) *(f32x4*)(tailu + ((size_t)blk * 3 + (fr - 13)) * LW + c0 + 4 * n) = gv;
;                         }
;                         if (!(m == 0 && fr < 3)) {
;                             u32x4 w; w.x = cvt_pk_bf16(o[0][0], o[0][1]); w.y = cvt_pk_bf16(o[0][2], o[0][3]); w.z = cvt_pk_bf16(o[1][0], o[1][1]); w.w = cvt_pk_bf16(o[1][2], o[1][3]);
;                             *(u32x4*)(vout + (size_t)row * LW + c0) = w;
	v_pk_fma_f32 v[138:139], v[78:79], v[138:139], v[82:83]
	s_nop 1
	v_mov_b32_dpp v140, v48 row_ror:3 row_mask:0xf bank_mask:0xf
	v_mov_b32_dpp v143, v49 row_ror:3 row_mask:0xf bank_mask:0xf
	v_mov_b32_dpp v144, v50 row_ror:1 row_mask:0xf bank_mask:0xf
	v_mov_b32_dpp v146, v50 row_ror:3 row_mask:0xf bank_mask:0xf
	v_mov_b32_dpp v147, v51 row_ror:1 row_mask:0xf bank_mask:0xf
	v_mov_b32_dpp v161, v51 row_ror:3 row_mask:0xf bank_mask:0xf
	v_cndmask_b32_e64 v61, v141, v153, s[4:5]
	v_cndmask_b32_e32 v62, v142, v154, vcc
	v_cndmask_b32_e32 v63, v145, v157, vcc
	v_pk_fma_f32 v[136:137], v[74:75], v[136:137], v[138:139]
	s_nop 1
	v_mov_b32_dpp v138, v48 row_ror:1 row_mask:0xf bank_mask:0xf
	v_mov_b32_dpp v139, v48 row_ror:2 row_mask:0xf bank_mask:0xf
	v_mov_b32_dpp v141, v49 row_ror:1 row_mask:0xf bank_mask:0xf
	v_mov_b32_dpp v142, v49 row_ror:2 row_mask:0xf bank_mask:0xf
	v_mov_b32_dpp v145, v50 row_ror:2 row_mask:0xf bank_mask:0xf
	v_mov_b32_dpp v160, v51 row_ror:2 row_mask:0xf bank_mask:0xf
	v_pk_fma_f32 v[60:61], v[76:77], v[60:61], v[80:81]
	s_nop 0
	v_pk_fma_f32 v[58:59], v[72:73], v[58:59], v[60:61]
	v_cndmask_b32_e64 v60, v132, v140, s[4:5]
	v_pk_fma_f32 v[56:57], v[68:69], v[56:57], v[58:59]
	v_pk_fma_f32 v[58:59], v[70:71], v[62:63], v[136:137]
	v_cndmask_b32_e64 v61, v133, v143, s[4:5]
	v_cndmask_b32_e32 v62, v126, v144, vcc
	v_cndmask_b32_e64 v126, v134, v146, s[4:5]
	v_cndmask_b32_e32 v63, v127, v147, vcc
	v_cndmask_b32_e64 v127, v135, v161, s[4:5]
	v_pk_fma_f32 v[54:55], v[54:55], v[66:67], v[58:59]
	v_pk_fma_f32 v[52:53], v[52:53], v[64:65], v[56:57]
	v_cndmask_b32_e32 v56, v124, v138, vcc
	v_cndmask_b32_e64 v58, v128, v139, s[0:1]
	v_cndmask_b32_e32 v57, v125, v141, vcc
	v_cndmask_b32_e64 v59, v129, v142, s[0:1]
	v_cndmask_b32_e64 v124, v130, v145, s[0:1]
	v_cndmask_b32_e64 v125, v131, v160, s[0:1]
	v_pk_fma_f32 v[60:61], v[96:97], v[60:61], v[100:101]
	v_pk_fma_f32 v[126:127], v[98:99], v[126:127], v[102:103]
	v_pk_fma_f32 v[58:59], v[92:93], v[58:59], v[60:61]
	v_pk_fma_f32 v[124:125], v[94:95], v[124:125], v[126:127]
	v_pk_fma_f32 v[56:57], v[88:89], v[56:57], v[58:59]
	v_pk_fma_f32 v[58:59], v[90:91], v[62:63], v[124:125]
	s_nop 0
	v_pk_fma_f32 v[58:59], v[50:51], v[86:87], v[58:59]
	v_pk_fma_f32 v[50:51], v[48:49], v[84:85], v[56:57]
	v_cvt_pk_bf16_f32 v48, v52, v53
	v_cvt_pk_bf16_f32 v49, v54, v55
	s_nop 1
	v_mov_b32_dpp v53, v45 row_ror:3 row_mask:0xf bank_mask:0xf
	v_cvt_pk_bf16_f32 v50, v50, v51
	v_cvt_pk_bf16_f32 v51, v58, v59
	global_store_dwordx4 v[112:113], v[48:51], off offset:256
	s_nop 1
	v_mov_b32_dpp v50, v44 row_ror:3 row_mask:0xf bank_mask:0xf
	v_mov_b32_dpp v56, v46 row_ror:3 row_mask:0xf bank_mask:0xf
	v_mov_b32_dpp v59, v47 row_ror:3 row_mask:0xf bank_mask:0xf
	v_mov_b32_dpp v49, v44 row_ror:2 row_mask:0xf bank_mask:0xf
	v_mov_b32_dpp v52, v45 row_ror:2 row_mask:0xf bank_mask:0xf
	v_mov_b32_dpp v55, v46 row_ror:2 row_mask:0xf bank_mask:0xf
	v_mov_b32_dpp v58, v47 row_ror:2 row_mask:0xf bank_mask:0xf
	v_mov_b32_dpp v48, v44 row_ror:1 row_mask:0xf bank_mask:0xf
	v_mov_b32_dpp v51, v45 row_ror:1 row_mask:0xf bank_mask:0xf
	v_mov_b32_dpp v54, v46 row_ror:1 row_mask:0xf bank_mask:0xf
	v_mov_b32_dpp v57, v47 row_ror:1 row_mask:0xf bank_mask:0xf
	v_cndmask_b32_e64 v112, v150, v50, s[4:5]
	v_cndmask_b32_e64 v113, v153, v53, s[4:5]
	v_cndmask_b32_e64 v128, v156, v56, s[4:5]
	v_cndmask_b32_e64 v129, v159, v59, s[4:5]
	v_cndmask_b32_e64 v62, v149, v49, s[0:1]
	v_cndmask_b32_e64 v63, v152, v52, s[0:1]
	v_cndmask_b32_e64 v126, v155, v55, s[0:1]
	v_cndmask_b32_e64 v127, v158, v58, s[0:1]
	v_pk_fma_f32 v[112:113], v[76:77], v[112:113], v[80:81]
	v_pk_fma_f32 v[128:129], v[78:79], v[128:129], v[82:83]
	v_cndmask_b32_e32 v60, v148, v48, vcc
	v_cndmask_b32_e32 v61, v151, v51, vcc
	v_cndmask_b32_e32 v124, v154, v54, vcc
	v_cndmask_b32_e32 v125, v157, v57, vcc
	v_pk_fma_f32 v[126:127], v[74:75], v[126:127], v[128:129]
	v_pk_fma_f32 v[62:63], v[72:73], v[62:63], v[112:113]
	s_nop 1
	v_mov_b32_dpp v112, v42 row_ror:3 row_mask:0xf bank_mask:0xf
	v_pk_fma_f32 v[60:61], v[68:69], v[60:61], v[62:63]
	v_pk_fma_f32 v[62:63], v[70:71], v[124:125], v[126:127]
	v_pk_fma_f32 v[126:127], v[44:45], v[64:65], v[60:61]
	v_pk_fma_f32 v[136:137], v[46:47], v[66:67], v[62:63]
	s_nop 1
	v_mov_b32_dpp v46, v40 row_ror:3 row_mask:0xf bank_mask:0xf
	v_mov_b32_dpp v47, v41 row_ror:1 row_mask:0xf bank_mask:0xf
	v_mov_b32_dpp v61, v41 row_ror:3 row_mask:0xf bank_mask:0xf
	v_mov_b32_dpp v125, v43 row_ror:3 row_mask:0xf bank_mask:0xf
	v_mov_b32_dpp v44, v40 row_ror:1 row_mask:0xf bank_mask:0xf
	v_mov_b32_dpp v45, v40 row_ror:2 row_mask:0xf bank_mask:0xf
	v_mov_b32_dpp v60, v41 row_ror:2 row_mask:0xf bank_mask:0xf
	v_mov_b32_dpp v63, v42 row_ror:2 row_mask:0xf bank_mask:0xf
	v_mov_b32_dpp v124, v43 row_ror:2 row_mask:0xf bank_mask:0xf
	v_mov_b32_dpp v62, v42 row_ror:1 row_mask:0xf bank_mask:0xf
	v_mov_b32_dpp v113, v43 row_ror:1 row_mask:0xf bank_mask:0xf
	v_cndmask_b32_e64 v132, v140, v46, s[4:5]
	v_cndmask_b32_e32 v129, v141, v47, vcc
	v_cndmask_b32_e64 v133, v143, v61, s[4:5]
	v_cndmask_b32_e64 v140, v146, v112, s[4:5]
	v_cndmask_b32_e64 v141, v161, v125, s[4:5]
	v_cndmask_b32_e32 v128, v138, v44, vcc
	v_cndmask_b32_e64 v130, v139, v45, s[0:1]
	v_cndmask_b32_e64 v131, v142, v60, s[0:1]
	v_cndmask_b32_e64 v138, v145, v63, s[0:1]
	v_cndmask_b32_e64 v139, v160, v124, s[0:1]
	v_pk_fma_f32 v[132:133], v[96:97], v[132:133], v[100:101]
	v_pk_fma_f32 v[140:141], v[98:99], v[140:141], v[102:103]
	v_cndmask_b32_e32 v134, v144, v62, vcc
	v_cndmask_b32_e32 v135, v147, v113, vcc
	v_pk_fma_f32 v[138:139], v[94:95], v[138:139], v[140:141]
	v_pk_fma_f32 v[130:131], v[92:93], v[130:131], v[132:133]
	s_nop 1
	v_mov_b32_dpp v132, v35 row_ror:2 row_mask:0xf bank_mask:0xf
	v_pk_fma_f32 v[128:129], v[88:89], v[128:129], v[130:131]
	v_pk_fma_f32 v[130:131], v[90:91], v[134:135], v[138:139]
	v_pk_fma_f32 v[140:141], v[40:41], v[84:85], v[128:129]
	v_pk_fma_f32 v[138:139], v[42:43], v[86:87], v[130:131]
	v_cvt_pk_bf16_f32 v134, v126, v127
	s_nop 1
	v_mov_b32_dpp v40, v32 row_ror:1 row_mask:0xf bank_mask:0xf
	v_mov_b32_dpp v41, v32 row_ror:2 row_mask:0xf bank_mask:0xf
	v_mov_b32_dpp v42, v32 row_ror:3 row_mask:0xf bank_mask:0xf
	v_mov_b32_dpp v43, v33 row_ror:1 row_mask:0xf bank_mask:0xf
	v_mov_b32_dpp v126, v33 row_ror:2 row_mask:0xf bank_mask:0xf
	v_mov_b32_dpp v127, v33 row_ror:3 row_mask:0xf bank_mask:0xf
	v_mov_b32_dpp v128, v34 row_ror:1 row_mask:0xf bank_mask:0xf
	v_mov_b32_dpp v129, v34 row_ror:2 row_mask:0xf bank_mask:0xf
	v_mov_b32_dpp v130, v34 row_ror:3 row_mask:0xf bank_mask:0xf
	v_mov_b32_dpp v131, v35 row_ror:1 row_mask:0xf bank_mask:0xf
	v_mov_b32_dpp v133, v35 row_ror:3 row_mask:0xf bank_mask:0xf
	v_cvt_pk_bf16_f32 v135, v136, v137
	v_cvt_pk_bf16_f32 v136, v140, v141
	v_cvt_pk_bf16_f32 v137, v138, v139
	global_store_dwordx4 v[114:115], v[134:137], off offset:256
	s_and_saveexec_b64 s[12:13], s[6:7]
	s_cbranch_execz .LBB0_164
	global_store_dwordx4 v[108:109], v[32:35], off offset:512

; #define LAS __attribute__((address_space(3)))
; __global__ void __launch_bounds__(NTHR, 2) hybrid_block_fwd(Args a) {
;     extern __shared__ __attribute__((aligned(16))) unsigned char lds_raw[];
;     LAS unsigned char* lds = (LAS unsigned char*)lds_raw;
	.amdhsa_kernel _Z16hybrid_block_fwd4Args
		.amdhsa_group_segment_fixed_size 4096
		.amdhsa_private_segment_fixed_size 0
		.amdhsa_kernarg_size 448
		.amdhsa_user_sgpr_count 2
		.amdhsa_user_sgpr_dispatch_ptr 0
		.amdhsa_user_sgpr_queue_ptr 0
		.amdhsa_user_sgpr_kernarg_segment_ptr 1
		.amdhsa_user_sgpr_dispatch_id 0
		.amdhsa_user_sgpr_kernarg_preload_length 0
		.amdhsa_user_sgpr_kernarg_preload_offset 0
		.amdhsa_user_sgpr_private_segment_size 0
		.amdhsa_uses_dynamic_stack 0
		.amdhsa_enable_private_segment 0
		.amdhsa_system_sgpr_workgroup_id_x 1
		.amdhsa_system_sgpr_workgroup_id_y 0
		.amdhsa_system_sgpr_workgroup_id_z 0
		.amdhsa_system_sgpr_workgroup_info 0
		.amdhsa_system_vgpr_workitem_id 2
		.amdhsa_next_free_vgpr 249
		.amdhsa_next_free_sgpr 102
		.amdhsa_accum_offset 252
		.amdhsa_reserve_vcc 1
		.amdhsa_float_round_mode_32 0
		.amdhsa_float_round_mode_16_64 0
		.amdhsa_float_denorm_mode_32 3
		.amdhsa_float_denorm_mode_16_64 3
		.amdhsa_dx10_clamp 1
		.amdhsa_ieee_mode 1
		.amdhsa_fp16_overflow 0
		.amdhsa_tg_split 0
		.amdhsa_exception_fp_ieee_invalid_op 0
		.amdhsa_exception_fp_denorm_src 0
		.amdhsa_exception_fp_ieee_div_zero 0
		.amdhsa_exception_fp_ieee_overflow 0
		.amdhsa_exception_fp_ieee_underflow 0
		.amdhsa_exception_fp_ieee_inexact 0
		.amdhsa_exception_int_div_zero 0
	.end_amdhsa_kernel

; #define LAS __attribute__((address_space(3)))
; __global__ void __launch_bounds__(NTHR, 2) hybrid_block_fwd(Args a) {
;     extern __shared__ __attribute__((aligned(16))) unsigned char lds_raw[];
;     LAS unsigned char* lds = (LAS unsigned char*)lds_raw;
amdhsa.kernels:
  - .agpr_count:     0
    .args:
      - .offset:         0
        .size:           192
        .value_kind:     by_value
      - .offset:         192
        .size:           4
        .value_kind:     hidden_block_count_x
      - .offset:         196
        .size:           4
        .value_kind:     hidden_block_count_y
      - .offset:         200
        .size:           4
        .value_kind:     hidden_block_count_z
      - .offset:         204
        .size:           2
        .value_kind:     hidden_group_size_x
      - .offset:         206
        .size:           2
        .value_kind:     hidden_group_size_y
      - .offset:         208
        .size:           2
        .value_kind:     hidden_group_size_z
      - .offset:         210
        .size:           2
        .value_kind:     hidden_remainder_x
      - .offset:         212
        .size:           2
        .value_kind:     hidden_remainder_y
      - .offset:         214
        .size:           2
        .value_kind:     hidden_remainder_z
      - .offset:         232
        .size:           8
        .value_kind:     hidden_global_offset_x
      - .offset:         240
        .size:           8
        .value_kind:     hidden_global_offset_y
      - .offset:         248
        .size:           8
        .value_kind:     hidden_global_offset_z
      - .offset:         256
        .size:           2
        .value_kind:     hidden_grid_dims
      - .offset:         280
        .size:           8
        .value_kind:     hidden_multigrid_sync_arg
      - .offset:         312
        .size:           4
        .value_kind:     hidden_dynamic_lds_size
    .group_segment_fixed_size: 4096
    .kernarg_segment_align: 8
    .kernarg_segment_size: 448
    .language:       OpenCL C
    .language_version:
      - 2
      - 0
    .max_flat_workgroup_size: 512
    .name:           _Z16hybrid_block_fwd4Args
    .private_segment_fixed_size: 0
    .sgpr_count:     108
    .sgpr_spill_count: 38
    .symbol:         _Z16hybrid_block_fwd4Args.kd
    .uniform_work_group_size: 1
    .uses_dynamic_stack: false
    .vgpr_count:     249
    .vgpr_spill_count: 0
    .wavefront_size: 64
